# attention: window mask of the first/last key block folded into the QK MFMA accumulator input (per-lane +K/-inf and -K/-inf matrices built once per unit); generic per-element mask path and its dispatch
# baseline (speedup 1.0000x reference)
; #define LAS __attribute__((address_space(3)))
; __device__ __forceinline__ void attn_unit(LAS unsigned char* lds, const bf16* PROJ, bf16* DA, const float* sinkl, int unit, int tid, int wid, int lane) {
;     ...
;     const int s0 = (n - 1) * 128;
; #pragma unroll
;     for (int hp = 0; hp < 2; ++hp) {
;         v4u kreg[3], vreg[3];
; #pragma unroll
;         for (int i = 0; i < 3; ++i) {
;             const int idx = tid + 512 * (3 * hp + i), c = idx >> 3, ch = idx & 7, s = s0 + c;
;             if (s >= 0 && s < SEQ) { const bf16* p = PROJ + (rowb + s) * INW + 1024 + hk * 64 + ch * 8; kreg[i] = *(const v4u*)p; vreg[i] = *(const v4u*)(p + 128); }
;             else { kreg[i] = (v4u){0u, 0u, 0u, 0u}; vreg[i] = (v4u){0u, 0u, 0u, 0u}; }
;         }
; #pragma unroll
;         for (int i = 0; i < 3; ++i) {
;             const int idx = tid + 512 * (3 * hp + i), c = idx >> 3, ch = idx & 7;
;             *(LAS v4u*)(Ks + c * KS_PITCH + ch * 8) = kreg[i];
;             LAS bf16* vp = Vt + (ch * 8) * VT_PITCH + c;
;             vp[0 * VT_PITCH] = (bf16)(vreg[i].x & 0xffffu); vp[1 * VT_PITCH] = (bf16)(vreg[i].x >> 16);
;             vp[2 * VT_PITCH] = (bf16)(vreg[i].y & 0xffffu); vp[3 * VT_PITCH] = (bf16)(vreg[i].y >> 16);
;             vp[4 * VT_PITCH] = (bf16)(vreg[i].z & 0xffffu); vp[5 * VT_PITCH] = (bf16)(vreg[i].z >> 16);
;             vp[6 * VT_PITCH] = (bf16)(vreg[i].w & 0xffffu); vp[7 * VT_PITCH] = (bf16)(vreg[i].w >> 16);
;         }
;     }
;     __syncthreads();
.LBB0_355:
	s_and_b64 vcc, exec, s[36:37]
	s_cbranch_vccz .LBB0_423
	v_lshlrev_b32_e32 v2, 3, v173
	v_ashrrev_i32_e32 v42, 3, v173
	v_readlane_b32 s13, v239, 10
	v_and_b32_e32 v41, 56, v2
	v_lshlrev_b32_e32 v38, 1, v41
	v_mov_b32_e32 v39, v66
	s_waitcnt lgkmcnt(0)
	v_readlane_b32 s6, v239, 6
	v_readlane_b32 s7, v239, 7
	v_readlane_b32 s12, v239, 9
	s_lshl_b64 s[24:25], s[70:71], 2
	v_readlane_b32 s32, v239, 11
	s_add_u32 s24, s32, s24
	v_readlane_b32 s32, v239, 12
	s_addc_u32 s25, s32, s25
	v_readlane_b32 s88, v238, 7
	v_readlane_b32 s89, v238, 8
	v_bfe_u32 v189, v173, 5, 1
	v_lshlrev_b32_e32 v192, 4, v189
	v_mov_b32_e32 v193, v66
	v_lshl_add_u64 v[192:193], s[88:89], 0, v[192:193]
	v_and_b32_e32 v189, 31, v173
	v_or_b32_e32 v189, s80, v189
	v_or_b32_e32 v189, s12, v189
	v_or_b32_e32 v189, s6, v189
	v_mad_u64_u32 v[192:193], s[88:89], v189, s82, v[192:193]
	v_mad_i32_i24 v193, s7, v201, v193
	global_load_dwordx4 v[68:71], v[192:193], off offset:1024
	global_load_dwordx4 v[72:75], v[192:193], off offset:1056
	global_load_dwordx4 v[76:79], v[192:193], off offset:1088
	global_load_dwordx4 v[80:83], v[192:193], off offset:1120
	global_load_dword v191, v66, s[24:25]
	v_readlane_b32 s72, v238, 5
	v_readlane_b32 s73, v238, 6
	s_movk_i32 s84, 0x1000
	v_add_u32_e32 v2, 0x200, v173
	v_ashrrev_i32_e32 v43, 3, v2
	v_add_u32_e32 v2, 0x400, v173
	v_ashrrev_i32_e32 v44, 3, v2
	v_add_u32_e32 v2, 0x600, v173
	v_ashrrev_i32_e32 v186, 3, v2
	v_add_u32_e32 v2, 0x800, v173
	v_ashrrev_i32_e32 v187, 3, v2
	v_add_u32_e32 v2, 0xa00, v173
	v_ashrrev_i32_e32 v188, 3, v2
	v_add_u32_e32 v189, s13, v42
	v_cmp_gt_u32_e64 s[28:29], s84, v189
	v_and_b32_e32 v189, 0xfff, v189
	v_or_b32_e32 v190, s6, v189
	v_mov_b64_e32 v[192:193], s[72:73]
	v_mad_u64_u32 v[192:193], s[88:89], v190, s82, v[192:193]
	v_mad_i32_i24 v193, s7, v201, v193
	v_lshl_add_u64 v[192:193], v[192:193], 0, v[38:39]
	global_load_dwordx4 v[26:29], v[192:193], off offset:2048
	global_load_dwordx4 v[174:177], v[192:193], off offset:2304
	v_add_u32_e32 v189, s13, v43
	v_cmp_gt_u32_e64 s[30:31], s84, v189
	v_and_b32_e32 v189, 0xfff, v189
	v_or_b32_e32 v190, s6, v189
	v_mov_b64_e32 v[192:193], s[72:73]
	v_mad_u64_u32 v[192:193], s[88:89], v190, s82, v[192:193]
	v_mad_i32_i24 v193, s7, v201, v193
	v_lshl_add_u64 v[192:193], v[192:193], 0, v[38:39]
	global_load_dwordx4 v[30:33], v[192:193], off offset:2048
	global_load_dwordx4 v[178:181], v[192:193], off offset:2304
	v_add_u32_e32 v189, s13, v44
	v_cmp_gt_u32_e64 s[34:35], s84, v189
	v_and_b32_e32 v189, 0xfff, v189
	v_or_b32_e32 v190, s6, v189
	v_mov_b64_e32 v[192:193], s[72:73]
	v_mad_u64_u32 v[192:193], s[88:89], v190, s82, v[192:193]
	v_mad_i32_i24 v193, s7, v201, v193
	v_lshl_add_u64 v[192:193], v[192:193], 0, v[38:39]
	global_load_dwordx4 v[34:37], v[192:193], off offset:2048
	global_load_dwordx4 v[182:185], v[192:193], off offset:2304
	v_add_u32_e32 v189, s13, v186
	v_cmp_gt_u32_e64 s[62:63], s84, v189
	v_and_b32_e32 v189, 0xfff, v189
	v_or_b32_e32 v190, s6, v189
	v_mov_b64_e32 v[192:193], s[72:73]
	v_mad_u64_u32 v[192:193], s[88:89], v190, s82, v[192:193]
	v_mad_i32_i24 v193, s7, v201, v193
	v_lshl_add_u64 v[192:193], v[192:193], 0, v[38:39]
	global_load_dwordx4 v[6:9], v[192:193], off offset:2048
	global_load_dwordx4 v[2:5], v[192:193], off offset:2304
	v_add_u32_e32 v189, s13, v187
	v_cmp_gt_u32_e64 s[74:75], s84, v189
	v_and_b32_e32 v189, 0xfff, v189
	v_or_b32_e32 v190, s6, v189
	v_mov_b64_e32 v[192:193], s[72:73]
	v_mad_u64_u32 v[192:193], s[88:89], v190, s82, v[192:193]
	v_mad_i32_i24 v193, s7, v201, v193
	v_lshl_add_u64 v[192:193], v[192:193], 0, v[38:39]
	global_load_dwordx4 v[14:17], v[192:193], off offset:2048
	global_load_dwordx4 v[10:13], v[192:193], off offset:2304
	v_add_u32_e32 v189, s13, v188
	v_cmp_gt_u32_e64 s[76:77], s84, v189
	v_and_b32_e32 v189, 0xfff, v189
	v_or_b32_e32 v190, s6, v189
	v_mov_b64_e32 v[192:193], s[72:73]
	v_mad_u64_u32 v[192:193], s[88:89], v190, s82, v[192:193]
	v_mad_i32_i24 v193, s7, v201, v193
	v_lshl_add_u64 v[192:193], v[192:193], 0, v[38:39]
	global_load_dwordx4 v[22:25], v[192:193], off offset:2048
	global_load_dwordx4 v[18:21], v[192:193], off offset:2304
	v_lshl_add_u32 v40, v41, 1, 0
	s_movk_i32 s32, 0x306
	v_mad_u32_u24 v41, v41, s32, v40
	v_and_b32_e32 v123, 8, v173
	v_cmp_eq_u32_e64 s[98:99], 0, v123
	v_mov_b32_e32 v136, 0x01000504
	v_mov_b32_e32 v137, 0x03020706
	v_mov_b32_e32 v138, 0x05040100
	v_cndmask_b32_e64 v136, v136, v138, s[98:99]
	v_mov_b32_e32 v138, 0x07060302
	v_cndmask_b32_e64 v137, v137, v138, s[98:99]
	v_mov_b32_e32 v138, 0xc20
	v_cndmask_b32_e64 v138, v138, 0, s[98:99]
	v_add_u32_e32 v138, v41, v138
	s_waitcnt vmcnt(11)
	v_cndmask_b32_e64 v26, 0, v26, s[28:29]
	v_cndmask_b32_e64 v27, 0, v27, s[28:29]
	v_cndmask_b32_e64 v28, 0, v28, s[28:29]
	v_cndmask_b32_e64 v29, 0, v29, s[28:29]
	v_mad_u32_u24 v121, v42, s3, v40
	ds_write_b128 v121, v[26:29]
	s_waitcnt vmcnt(10)
	v_cndmask_b32_e64 v174, 0, v174, s[28:29]
	v_cndmask_b32_e64 v175, 0, v175, s[28:29]
	v_cndmask_b32_e64 v176, 0, v176, s[28:29]
	v_cndmask_b32_e64 v177, 0, v177, s[28:29]
	v_and_b32_e32 v123, -2, v42
	v_lshl_add_u32 v122, v123, 1, v138
	s_nop 0
	v_mov_b32_dpp v124, v174 row_ror:8 row_mask:0xf bank_mask:0xf
	v_mov_b32_dpp v125, v175 row_ror:8 row_mask:0xf bank_mask:0xf
	v_mov_b32_dpp v126, v176 row_ror:8 row_mask:0xf bank_mask:0xf
	v_mov_b32_dpp v127, v177 row_ror:8 row_mask:0xf bank_mask:0xf
	v_cndmask_b32_e64 v128, v176, v174, s[98:99]
	v_cndmask_b32_e64 v129, v177, v175, s[98:99]
	v_cndmask_b32_e64 v130, v126, v124, s[98:99]
	v_cndmask_b32_e64 v131, v127, v125, s[98:99]
	v_perm_b32 v132, v130, v128, v136
	v_perm_b32 v133, v130, v128, v137
	v_perm_b32 v134, v131, v129, v136
	v_perm_b32 v135, v131, v129, v137
	ds_write_b32 v122, v132 offset:55296
	ds_write_b32 v122, v133 offset:56072
	ds_write_b32 v122, v134 offset:56848
	ds_write_b32 v122, v135 offset:57624
	s_waitcnt vmcnt(9)
; #define LAS __attribute__((address_space(3)))
; __device__ __forceinline__ void attn_unit(LAS unsigned char* lds, const bf16* PROJ, bf16* DA, const float* sinkl, int unit, int tid, int wid, int lane) {
;     ...
; #pragma unroll
;         for (int i = 0; i < 3; ++i) {
;             const int idx = tid + 512 * (3 * hp + i), c = idx >> 3, ch = idx & 7;
;             *(LAS v4u*)(Ks + c * KS_PITCH + ch * 8) = kreg[i];
;             LAS bf16* vp = Vt + (ch * 8) * VT_PITCH + c;
;             vp[0 * VT_PITCH] = (bf16)(vreg[i].x & 0xffffu); vp[1 * VT_PITCH] = (bf16)(vreg[i].x >> 16);
;             vp[2 * VT_PITCH] = (bf16)(vreg[i].y & 0xffffu); vp[3 * VT_PITCH] = (bf16)(vreg[i].y >> 16);
;             vp[4 * VT_PITCH] = (bf16)(vreg[i].z & 0xffffu); vp[5 * VT_PITCH] = (bf16)(vreg[i].z >> 16);
;             vp[6 * VT_PITCH] = (bf16)(vreg[i].w & 0xffffu); vp[7 * VT_PITCH] = (bf16)(vreg[i].w >> 16);
;         }
;     }
;     __syncthreads();
	v_cndmask_b32_e64 v30, 0, v30, s[30:31]
	v_cndmask_b32_e64 v31, 0, v31, s[30:31]
	v_cndmask_b32_e64 v32, 0, v32, s[30:31]
	v_cndmask_b32_e64 v33, 0, v33, s[30:31]
	v_mad_u32_u24 v121, v43, s3, v40
	ds_write_b128 v121, v[30:33]
	s_waitcnt vmcnt(8)
	v_cndmask_b32_e64 v178, 0, v178, s[30:31]
	v_cndmask_b32_e64 v179, 0, v179, s[30:31]
	v_cndmask_b32_e64 v180, 0, v180, s[30:31]
	v_cndmask_b32_e64 v181, 0, v181, s[30:31]
	v_and_b32_e32 v123, -2, v43
	v_lshl_add_u32 v122, v123, 1, v138
	s_nop 0
	v_mov_b32_dpp v124, v178 row_ror:8 row_mask:0xf bank_mask:0xf
	v_mov_b32_dpp v125, v179 row_ror:8 row_mask:0xf bank_mask:0xf
	v_mov_b32_dpp v126, v180 row_ror:8 row_mask:0xf bank_mask:0xf
	v_mov_b32_dpp v127, v181 row_ror:8 row_mask:0xf bank_mask:0xf
	v_cndmask_b32_e64 v128, v180, v178, s[98:99]
	v_cndmask_b32_e64 v129, v181, v179, s[98:99]
	v_cndmask_b32_e64 v130, v126, v124, s[98:99]
	v_cndmask_b32_e64 v131, v127, v125, s[98:99]
	v_perm_b32 v132, v130, v128, v136
	v_perm_b32 v133, v130, v128, v137
	v_perm_b32 v134, v131, v129, v136
	v_perm_b32 v135, v131, v129, v137
	ds_write_b32 v122, v132 offset:55296
	ds_write_b32 v122, v133 offset:56072
	ds_write_b32 v122, v134 offset:56848
	ds_write_b32 v122, v135 offset:57624
	s_waitcnt vmcnt(7)
	v_cndmask_b32_e64 v34, 0, v34, s[34:35]
	v_cndmask_b32_e64 v35, 0, v35, s[34:35]
	v_cndmask_b32_e64 v36, 0, v36, s[34:35]
	v_cndmask_b32_e64 v37, 0, v37, s[34:35]
	v_mad_u32_u24 v121, v44, s3, v40
	ds_write_b128 v121, v[34:37]
	s_waitcnt vmcnt(6)
	v_cndmask_b32_e64 v182, 0, v182, s[34:35]
	v_cndmask_b32_e64 v183, 0, v183, s[34:35]
	v_cndmask_b32_e64 v184, 0, v184, s[34:35]
	v_cndmask_b32_e64 v185, 0, v185, s[34:35]
	v_and_b32_e32 v123, -2, v44
	v_lshl_add_u32 v122, v123, 1, v138
	s_nop 0
	v_mov_b32_dpp v124, v182 row_ror:8 row_mask:0xf bank_mask:0xf
	v_mov_b32_dpp v125, v183 row_ror:8 row_mask:0xf bank_mask:0xf
	v_mov_b32_dpp v126, v184 row_ror:8 row_mask:0xf bank_mask:0xf
	v_mov_b32_dpp v127, v185 row_ror:8 row_mask:0xf bank_mask:0xf
	v_cndmask_b32_e64 v128, v184, v182, s[98:99]
	v_cndmask_b32_e64 v129, v185, v183, s[98:99]
	v_cndmask_b32_e64 v130, v126, v124, s[98:99]
	v_cndmask_b32_e64 v131, v127, v125, s[98:99]
	v_perm_b32 v132, v130, v128, v136
	v_perm_b32 v133, v130, v128, v137
	v_perm_b32 v134, v131, v129, v136
	v_perm_b32 v135, v131, v129, v137
	ds_write_b32 v122, v132 offset:55296
	ds_write_b32 v122, v133 offset:56072
	ds_write_b32 v122, v134 offset:56848
	ds_write_b32 v122, v135 offset:57624
	s_waitcnt vmcnt(5)
	v_cndmask_b32_e64 v6, 0, v6, s[62:63]
	v_cndmask_b32_e64 v7, 0, v7, s[62:63]
	v_cndmask_b32_e64 v8, 0, v8, s[62:63]
	v_cndmask_b32_e64 v9, 0, v9, s[62:63]
	v_mad_u32_u24 v121, v186, s3, v40
	ds_write_b128 v121, v[6:9]
	s_waitcnt vmcnt(4)
	v_cndmask_b32_e64 v2, 0, v2, s[62:63]
	v_cndmask_b32_e64 v3, 0, v3, s[62:63]
	v_cndmask_b32_e64 v4, 0, v4, s[62:63]
	v_cndmask_b32_e64 v5, 0, v5, s[62:63]
	v_and_b32_e32 v123, -2, v186
	v_lshl_add_u32 v122, v123, 1, v138
	s_nop 0
	v_mov_b32_dpp v124, v2 row_ror:8 row_mask:0xf bank_mask:0xf
	v_mov_b32_dpp v125, v3 row_ror:8 row_mask:0xf bank_mask:0xf
	v_mov_b32_dpp v126, v4 row_ror:8 row_mask:0xf bank_mask:0xf
	v_mov_b32_dpp v127, v5 row_ror:8 row_mask:0xf bank_mask:0xf
	v_cndmask_b32_e64 v128, v4, v2, s[98:99]
	v_cndmask_b32_e64 v129, v5, v3, s[98:99]
	v_cndmask_b32_e64 v130, v126, v124, s[98:99]
	v_cndmask_b32_e64 v131, v127, v125, s[98:99]
	v_perm_b32 v132, v130, v128, v136
	v_perm_b32 v133, v130, v128, v137
	v_perm_b32 v134, v131, v129, v136
	v_perm_b32 v135, v131, v129, v137
	ds_write_b32 v122, v132 offset:55296
	ds_write_b32 v122, v133 offset:56072
	ds_write_b32 v122, v134 offset:56848
	ds_write_b32 v122, v135 offset:57624
	s_waitcnt vmcnt(3)
	v_cndmask_b32_e64 v14, 0, v14, s[74:75]
	v_cndmask_b32_e64 v15, 0, v15, s[74:75]
	v_cndmask_b32_e64 v16, 0, v16, s[74:75]
	v_cndmask_b32_e64 v17, 0, v17, s[74:75]
	v_mad_u32_u24 v121, v187, s3, v40
	ds_write_b128 v121, v[14:17]
	s_waitcnt vmcnt(2)
	v_cndmask_b32_e64 v10, 0, v10, s[74:75]
	v_cndmask_b32_e64 v11, 0, v11, s[74:75]
	v_cndmask_b32_e64 v12, 0, v12, s[74:75]
	v_cndmask_b32_e64 v13, 0, v13, s[74:75]
	v_and_b32_e32 v123, -2, v187
	v_lshl_add_u32 v122, v123, 1, v138
	s_nop 0
	v_mov_b32_dpp v124, v10 row_ror:8 row_mask:0xf bank_mask:0xf
	v_mov_b32_dpp v125, v11 row_ror:8 row_mask:0xf bank_mask:0xf
	v_mov_b32_dpp v126, v12 row_ror:8 row_mask:0xf bank_mask:0xf
	v_mov_b32_dpp v127, v13 row_ror:8 row_mask:0xf bank_mask:0xf
	v_cndmask_b32_e64 v128, v12, v10, s[98:99]
	v_cndmask_b32_e64 v129, v13, v11, s[98:99]
	v_cndmask_b32_e64 v130, v126, v124, s[98:99]
	v_cndmask_b32_e64 v131, v127, v125, s[98:99]
	v_perm_b32 v132, v130, v128, v136
	v_perm_b32 v133, v130, v128, v137
	v_perm_b32 v134, v131, v129, v136
	v_perm_b32 v135, v131, v129, v137
	ds_write_b32 v122, v132 offset:55296
	ds_write_b32 v122, v133 offset:56072
	ds_write_b32 v122, v134 offset:56848
	ds_write_b32 v122, v135 offset:57624
	s_waitcnt vmcnt(1)
	v_cndmask_b32_e64 v22, 0, v22, s[76:77]
	v_cndmask_b32_e64 v23, 0, v23, s[76:77]
	v_cndmask_b32_e64 v24, 0, v24, s[76:77]
	v_cndmask_b32_e64 v25, 0, v25, s[76:77]
	v_mad_u32_u24 v121, v188, s3, v40
	ds_write_b128 v121, v[22:25]
	s_waitcnt vmcnt(0)
	v_cndmask_b32_e64 v18, 0, v18, s[76:77]
	v_cndmask_b32_e64 v19, 0, v19, s[76:77]
	v_cndmask_b32_e64 v20, 0, v20, s[76:77]
	v_cndmask_b32_e64 v21, 0, v21, s[76:77]
	v_and_b32_e32 v123, -2, v188
	v_lshl_add_u32 v122, v123, 1, v138
	s_nop 0
	v_mov_b32_dpp v124, v18 row_ror:8 row_mask:0xf bank_mask:0xf
	v_mov_b32_dpp v125, v19 row_ror:8 row_mask:0xf bank_mask:0xf
	v_mov_b32_dpp v126, v20 row_ror:8 row_mask:0xf bank_mask:0xf
	v_mov_b32_dpp v127, v21 row_ror:8 row_mask:0xf bank_mask:0xf
	v_cndmask_b32_e64 v128, v20, v18, s[98:99]
	v_cndmask_b32_e64 v129, v21, v19, s[98:99]
	v_cndmask_b32_e64 v130, v126, v124, s[98:99]
	v_cndmask_b32_e64 v131, v127, v125, s[98:99]
	v_perm_b32 v132, v130, v128, v136
	v_perm_b32 v133, v130, v128, v137
	v_perm_b32 v134, v131, v129, v136
	v_perm_b32 v135, v131, v129, v137
	ds_write_b32 v122, v132 offset:55296
	ds_write_b32 v122, v133 offset:56072
	ds_write_b32 v122, v134 offset:56848
	ds_write_b32 v122, v135 offset:57624
	s_waitcnt lgkmcnt(0)
	s_barrier
; #define ATT_QK(dst, cblk) do { _Pragma("unroll") for (int r = 0; r < 16; ++r) dst[r] = 0.f; \
;             _Pragma("unroll") for (int ks = 0; ks < 4; ++ks) { const bf16x8 kf = *(const LAS bf16x8*)(Ks + ((cblk) + r32) * KS_PITCH + ks * 16 + hi * 8); \
;                 dst = __builtin_amdgcn_mfma_f32_32x32x16_bf16(kf, qf[ks], dst, 0, 0, 0); } } while (0)
; __device__ __forceinline__ void attn_unit(LAS unsigned char* lds, const bf16* PROJ, bf16* DA, const float* sinkl, int unit, int tid, int wid, int lane) {
;     ...
;         const float fb0 = (float)(r32 + 128 - 4 * hi);
;         f32x16 pn;
;     ...
;         ATT_QK(pn, a0);
; #pragma unroll 1
;         for (int i = 0; i < 9; ++i) {
;             const int c0 = a0 + 32 * i;
;             f32x16 p = pn;
;             if (i < 8) ATT_QK(pn, c0 + 32);
;             const float fb = fb0 - (float)(32 * i);
;             const int sb0 = s0 + c0 + 4 * hi;
;             const float kmin = fmaxf(fb - 128.0f, (float)(-sb0)), kmax = fminf(fb + 128.0f, (float)(SEQ - 1 - sb0));
;             const float kmid = 0.5f * (kmin + kmax), khw = 0.5f * (kmax - kmin);
;             float mx = NEG;
; #pragma unroll
;             for (int r = 0; r < 16; ++r) { const float kr = (float)((r & 3) + 8 * (r >> 2)); p[r] = p[r] - slope2 * fabsf(fb - kr); }
;             if ((i == 0) || (i == 8) || edge_n) {
; #pragma unroll
;                 for (int r = 0; r < 16; ++r) { const float kr = (float)((r & 3) + 8 * (r >> 2)); p[r] = (fabsf(kr - kmid) <= khw) ? p[r] : NEG; }
	v_mul_f32_e32 v204, 0x00000000, v162
	v_mul_f32_e32 v205, 0x3f800000, v162
	v_mul_f32_e32 v206, 0x40000000, v162
	v_mul_f32_e32 v207, 0x40400000, v162
	v_mul_f32_e32 v208, 0x41000000, v162
	v_mul_f32_e32 v209, 0x41100000, v162
	v_mul_f32_e32 v210, 0x41200000, v162
	v_mul_f32_e32 v211, 0x41300000, v162
	v_mul_f32_e32 v212, 0x41800000, v162
	v_mul_f32_e32 v213, 0x41880000, v162
	v_mul_f32_e32 v214, 0x41900000, v162
	v_mul_f32_e32 v215, 0x41980000, v162
	v_mul_f32_e32 v216, 0x41c00000, v162
	v_mul_f32_e32 v217, 0x41c80000, v162
	v_mul_f32_e32 v218, 0x41d00000, v162
	v_mul_f32_e32 v219, 0x41d80000, v162
	v_mul_f32_e32 v220, 0x80000000, v162
	v_mul_f32_e32 v221, 0xbf800000, v162
	v_mul_f32_e32 v222, 0xc0000000, v162
	v_mul_f32_e32 v223, 0xc0400000, v162
	v_mul_f32_e32 v224, 0xc1000000, v162
	v_mul_f32_e32 v225, 0xc1100000, v162
	v_mul_f32_e32 v226, 0xc1200000, v162
	v_mul_f32_e32 v227, 0xc1300000, v162
	v_mul_f32_e32 v228, 0xc1800000, v162
	v_mul_f32_e32 v229, 0xc1880000, v162
	v_mul_f32_e32 v230, 0xc1900000, v162
	v_mul_f32_e32 v231, 0xc1980000, v162
	v_mul_f32_e32 v232, 0xc1c00000, v162
	v_mul_f32_e32 v233, 0xc1c80000, v162
	v_mul_f32_e32 v234, 0xc1d00000, v162
	v_mul_f32_e32 v235, 0xc1d80000, v162
	v_and_b32_e32 v67, 63, v173
	v_bfe_u32 v2, v173, 5, 1
	v_readlane_b32 s24, v238, 7
	v_and_b32_e32 v85, 31, v173
	v_lshlrev_b32_e32 v4, 3, v2
	v_lshlrev_b32_e32 v5, 2, v2
	v_lshlrev_b32_e32 v2, 4, v2
	v_or_b32_e32 v6, 32, v67
	v_readlane_b32 s25, v238, 8
	v_mul_u32_u24_e32 v7, 0x308, v85
	v_mul_u32_u24_e32 v8, 0x308, v6
	v_readlane_b32 s13, v238, 15
	v_add_u32_e32 v84, 0, v2
	v_sub_u32_e32 v95, v85, v5
	v_cvt_f32_i32_e32 v147, v95
	v_cmp_ge_f32_e32 vcc, 0x00000000, v147
	s_nop 1
	v_cndmask_b32_e32 v34, v202, v204, vcc
	v_cmp_le_f32_e32 vcc, 0x00000000, v147
	s_nop 1
	v_cndmask_b32_e32 v106, v202, v220, vcc
	v_cmp_ge_f32_e32 vcc, 0x3f800000, v147
	s_nop 1
	v_cndmask_b32_e32 v35, v202, v205, vcc
	v_cmp_le_f32_e32 vcc, 0x3f800000, v147
	s_nop 1
	v_cndmask_b32_e32 v107, v202, v221, vcc
	v_cmp_ge_f32_e32 vcc, 0x40000000, v147
	s_nop 1
	v_cndmask_b32_e32 v36, v202, v206, vcc
	v_cmp_le_f32_e32 vcc, 0x40000000, v147
	s_nop 1
	v_cndmask_b32_e32 v108, v202, v222, vcc
	v_cmp_ge_f32_e32 vcc, 0x40400000, v147
	s_nop 1
	v_cndmask_b32_e32 v37, v202, v207, vcc
	v_cmp_le_f32_e32 vcc, 0x40400000, v147
	s_nop 1
	v_cndmask_b32_e32 v109, v202, v223, vcc
	v_cmp_ge_f32_e32 vcc, 0x41000000, v147
	s_nop 1
	v_cndmask_b32_e32 v38, v202, v208, vcc
	v_cmp_le_f32_e32 vcc, 0x41000000, v147
	s_nop 1
	v_cndmask_b32_e32 v110, v202, v224, vcc
	v_cmp_ge_f32_e32 vcc, 0x41100000, v147
	s_nop 1
	v_cndmask_b32_e32 v39, v202, v209, vcc
	v_cmp_le_f32_e32 vcc, 0x41100000, v147
	s_nop 1
	v_cndmask_b32_e32 v111, v202, v225, vcc
	v_cmp_ge_f32_e32 vcc, 0x41200000, v147
	s_nop 1
	v_cndmask_b32_e32 v40, v202, v210, vcc
	v_cmp_le_f32_e32 vcc, 0x41200000, v147
	s_nop 1
	v_cndmask_b32_e32 v112, v202, v226, vcc
	v_cmp_ge_f32_e32 vcc, 0x41300000, v147
	s_nop 1
	v_cndmask_b32_e32 v41, v202, v211, vcc
	v_cmp_le_f32_e32 vcc, 0x41300000, v147
	s_nop 1
	v_cndmask_b32_e32 v113, v202, v227, vcc
	v_cmp_ge_f32_e32 vcc, 0x41800000, v147
	s_nop 1
	v_cndmask_b32_e32 v42, v202, v212, vcc
	v_cmp_le_f32_e32 vcc, 0x41800000, v147
	s_nop 1
	v_cndmask_b32_e32 v114, v202, v228, vcc
	v_cmp_ge_f32_e32 vcc, 0x41880000, v147
	s_nop 1
	v_cndmask_b32_e32 v43, v202, v213, vcc
	v_cmp_le_f32_e32 vcc, 0x41880000, v147
	s_nop 1
	v_cndmask_b32_e32 v115, v202, v229, vcc
	v_cmp_ge_f32_e32 vcc, 0x41900000, v147
	s_nop 1
	v_cndmask_b32_e32 v44, v202, v214, vcc
	v_cmp_le_f32_e32 vcc, 0x41900000, v147
	s_nop 1
	v_cndmask_b32_e32 v116, v202, v230, vcc
	v_cmp_ge_f32_e32 vcc, 0x41980000, v147
	s_nop 1
	v_cndmask_b32_e32 v45, v202, v215, vcc
	v_cmp_le_f32_e32 vcc, 0x41980000, v147
	s_nop 1
	v_cndmask_b32_e32 v117, v202, v231, vcc
	v_cmp_ge_f32_e32 vcc, 0x41c00000, v147
	s_nop 1
	v_cndmask_b32_e32 v46, v202, v216, vcc
	v_cmp_le_f32_e32 vcc, 0x41c00000, v147
	s_nop 1
	v_cndmask_b32_e32 v118, v202, v232, vcc
	v_cmp_ge_f32_e32 vcc, 0x41c80000, v147
	s_nop 1
	v_cndmask_b32_e32 v47, v202, v217, vcc
	v_cmp_le_f32_e32 vcc, 0x41c80000, v147
	s_nop 1
	v_cndmask_b32_e32 v119, v202, v233, vcc
	v_cmp_ge_f32_e32 vcc, 0x41d00000, v147
	s_nop 1
	v_cndmask_b32_e32 v48, v202, v218, vcc
	v_cmp_le_f32_e32 vcc, 0x41d00000, v147
	s_nop 1
	v_cndmask_b32_e32 v120, v202, v234, vcc
	v_cmp_ge_f32_e32 vcc, 0x41d80000, v147
	s_nop 1
	v_cndmask_b32_e32 v49, v202, v219, vcc
	v_cmp_le_f32_e32 vcc, 0x41d80000, v147
	s_nop 1
	v_cndmask_b32_e32 v121, v202, v235, vcc
	v_add3_u32 v96, v8, v4, s13
	v_add3_u32 v97, v7, v4, s13
	v_readlane_b32 s13, v238, 19
	v_add_u32_e32 v99, s80, v6
	s_mov_b32 s36, 0
	v_sub_u32_e32 v98, s13, v5
	s_mov_b64 s[38:39], -1
	s_mov_b32 s23, 0
	v_mul_f32_e32 v94, 0x3fb8aa3b, v191
	v_mov_b32_e32 v3, v66
	v_lshl_add_u64 v[86:87], s[24:25], 0, v[2:3]
	v_readlane_b32 s24, v238, 9
	v_readlane_b32 s25, v238, 10
	s_nop 1
	v_lshl_add_u64 v[88:89], s[24:25], 0, v[2:3]
	s_branch .LBB0_380
; __device__ __forceinline__ unsigned cvtpk_rne(float lo, float hi) { f32x2_t v = {lo, hi}; bf16x2_t b = __builtin_convertvector(v, bf16x2_t); return __builtin_bit_cast(unsigned, b); }
; __device__ __forceinline__ void attn_unit(LAS unsigned char* lds, const bf16* PROJ, bf16* DA, const float* sinkl, int unit, int tid, int wid, int lane) {
;     ...
;         { const auto rr = __builtin_amdgcn_permlane32_swap(__float_as_uint(l), __float_as_uint(l), false, false); l = __uint_as_float(rr[0]) + __uint_as_float(rr[1]); }
;         const float inv = __builtin_amdgcn_rcpf(l + __builtin_amdgcn_exp2f(sink2 - mrun));
;         bf16* orow = DA + qrow * 1024 + 512 + hq * 64;
; #pragma unroll
;         for (int db = 0; db < 2; ++db)
; #pragma unroll
;             for (int rp = 0; rp < 2; ++rp) {
;                 const f32x16& oo = db == 0 ? o0 : o1; const int ra = 8 * rp, rb = 8 * rp + 4;
;                 unsigned ax = cvtpk_rne(oo[ra] * inv, oo[ra + 1] * inv), ay = cvtpk_rne(oo[ra + 2] * inv, oo[ra + 3] * inv);
;                 unsigned bx = cvtpk_rne(oo[rb] * inv, oo[rb + 1] * inv), by = cvtpk_rne(oo[rb + 2] * inv, oo[rb + 3] * inv);
;                 { const auto t = __builtin_amdgcn_permlane32_swap(ax, bx, false, false); ax = t[0]; bx = t[1]; }
;                 { const auto t = __builtin_amdgcn_permlane32_swap(ay, by, false, false); ay = t[0]; by = t[1]; }
;                 *(v4u*)(orow + 32 * db + 16 * rp + 8 * hi) = (v4u){ax, ay, bx, by};
;             }
.LBB0_379:
	v_sub_f32_e32 v157, v94, v103
	v_exp_f32_e32 v157, v157
	v_mov_b32_e32 v156, v93
	s_nop 1
	v_permlane32_swap_b32_e32 v93, v156
	v_add_f32_e32 v156, v93, v156
	v_add_f32_e32 v156, v157, v156
	v_rcp_f32_e32 v156, v156
	v_lshlrev_b64 v[158:159], 11, v[90:91]
	v_lshl_add_u64 v[158:159], v[88:89], 0, v[158:159]
	s_mov_b32 s23, 32
	v_pk_mul_f32 v[18:19], v[18:19], v[156:157] op_sel_hi:[1,0]
	v_pk_mul_f32 v[20:21], v[20:21], v[156:157] op_sel_hi:[1,0]
	v_pk_mul_f32 v[2:3], v[2:3], v[156:157] op_sel_hi:[1,0]
	v_pk_mul_f32 v[4:5], v[4:5], v[156:157] op_sel_hi:[1,0]
	v_cvt_pk_bf16_f32 v18, v18, v19
	v_cvt_pk_bf16_f32 v19, v20, v21
	v_pk_mul_f32 v[20:21], v[22:23], v[156:157] op_sel_hi:[1,0]
	v_pk_mul_f32 v[22:23], v[24:25], v[156:157] op_sel_hi:[1,0]
	v_cvt_pk_bf16_f32 v2, v2, v3
	v_cvt_pk_bf16_f32 v3, v4, v5
	v_pk_mul_f32 v[4:5], v[6:7], v[156:157] op_sel_hi:[1,0]
	v_pk_mul_f32 v[6:7], v[8:9], v[156:157] op_sel_hi:[1,0]
	v_cvt_pk_bf16_f32 v20, v20, v21
	v_cvt_pk_bf16_f32 v21, v22, v23
	v_cvt_pk_bf16_f32 v4, v4, v5
	v_cvt_pk_bf16_f32 v5, v6, v7
	v_permlane32_swap_b32_e32 v18, v20
	v_permlane32_swap_b32_e32 v19, v21
	v_permlane32_swap_b32_e32 v2, v4
	v_permlane32_swap_b32_e32 v3, v5
	global_store_dwordx4 v[158:159], v[18:21], off offset:1024
	global_store_dwordx4 v[158:159], v[2:5], off offset:1088
	v_pk_mul_f32 v[22:23], v[32:33], v[156:157] op_sel_hi:[1,0]
	v_pk_mul_f32 v[18:19], v[26:27], v[156:157] op_sel_hi:[1,0]
	v_pk_mul_f32 v[20:21], v[28:29], v[156:157] op_sel_hi:[1,0]
	v_pk_mul_f32 v[2:3], v[10:11], v[156:157] op_sel_hi:[1,0]
	v_pk_mul_f32 v[4:5], v[12:13], v[156:157] op_sel_hi:[1,0]
	v_cvt_pk_bf16_f32 v18, v18, v19
	v_cvt_pk_bf16_f32 v19, v20, v21
	v_pk_mul_f32 v[20:21], v[30:31], v[156:157] op_sel_hi:[1,0]
	v_cvt_pk_bf16_f32 v2, v2, v3
	v_cvt_pk_bf16_f32 v3, v4, v5
	v_pk_mul_f32 v[4:5], v[14:15], v[156:157] op_sel_hi:[1,0]
	v_pk_mul_f32 v[6:7], v[16:17], v[156:157] op_sel_hi:[1,0]
	v_cvt_pk_bf16_f32 v20, v20, v21
	v_cvt_pk_bf16_f32 v21, v22, v23
	v_cvt_pk_bf16_f32 v4, v4, v5
	v_cvt_pk_bf16_f32 v5, v6, v7
	v_permlane32_swap_b32_e32 v18, v20
	v_permlane32_swap_b32_e32 v19, v21
	v_permlane32_swap_b32_e32 v2, v4
	v_permlane32_swap_b32_e32 v3, v5
	s_mov_b64 s[38:39], 0
	s_and_b64 vcc, exec, s[70:71]
	global_store_dwordx4 v[158:159], v[18:21], off offset:1056
	global_store_dwordx4 v[158:159], v[2:5], off offset:1120
	s_cbranch_vccnz .LBB0_392

; #define ATT_QK(dst, cblk) do { _Pragma("unroll") for (int r = 0; r < 16; ++r) dst[r] = 0.f; \
;             _Pragma("unroll") for (int ks = 0; ks < 4; ++ks) { const bf16x8 kf = *(const LAS bf16x8*)(Ks + ((cblk) + r32) * KS_PITCH + ks * 16 + hi * 8); \
;                 dst = __builtin_amdgcn_mfma_f32_32x32x16_bf16(kf, qf[ks], dst, 0, 0, 0); } } while (0)
; __device__ __forceinline__ void attn_unit(LAS unsigned char* lds, const bf16* PROJ, bf16* DA, const float* sinkl, int unit, int tid, int wid, int lane) {
;     ...
;         const int a0 = 64 * (wid & 1) + 32 * sb, a = a0 + r32;
;         const size_t qrow = rowb + (size_t)n * 128 + a;
;         bf16x8 qf[4];
; #pragma unroll
;         for (int ks = 0; ks < 4; ++ks) qf[ks] = *(const bf16x8*)(PROJ + qrow * INW + 512 + hq * 64 + ks * 16 + hi * 8);
;         float mrun = sink2, l = 0.f;
;         f32x16 o0, o1;
; #pragma unroll
;         for (int r = 0; r < 16; ++r) { o0[r] = 0.f; o1[r] = 0.f; }
;         const float fb0 = (float)(r32 + 128 - 4 * hi);
;         f32x16 pn;
;     ...
;         ATT_QK(pn, a0);
.Lq_skip1:
	v_mad_u32_u24 v26, v4, s3, v84
	ds_read_b128 v[18:21], v26
	ds_read_b128 v[22:25], v26 offset:32
	s_mov_b32 s37, s36
	s_xor_b64 s[70:71], s[38:39], -1
	s_mov_b32 s38, s36
	s_mov_b32 s39, s36
	s_mov_b32 s40, s36
	s_mov_b32 s41, s36
	s_mov_b32 s42, s36
	s_mov_b32 s43, s36
	s_mov_b32 s44, s36
	s_mov_b32 s45, s36
	s_mov_b32 s46, s36
	s_mov_b32 s47, s36
	s_mov_b32 s48, s36
	s_mov_b32 s49, s36
	s_mov_b32 s50, s36
	s_mov_b32 s51, s36
	v_mov_b64_e32 v[2:3], s[36:37]
	v_mov_b64_e32 v[16:17], s[50:51]
	s_lshl_b32 s24, s23, 1
	v_mov_b64_e32 v[4:5], s[38:39]
	v_mov_b64_e32 v[6:7], s[40:41]
	v_mov_b64_e32 v[8:9], s[42:43]
	v_mov_b64_e32 v[10:11], s[44:45]
	v_mov_b64_e32 v[12:13], s[46:47]
	v_mov_b64_e32 v[14:15], s[48:49]
	v_add_u32_e32 v100, s24, v96
	v_add_u32_e32 v101, s24, v97
	v_mov_b32_e32 v91, s7
	v_subrev_u32_e32 v102, s23, v98
	v_mov_b32_e32 v103, v94
	s_waitcnt vmcnt(3) lgkmcnt(1)
	v_mfma_f32_32x32x16_bf16 v[50:65], v[18:21], v[68:71], v[34:49]
	ds_read_b128 v[18:21], v26 offset:64
	s_waitcnt vmcnt(2) lgkmcnt(1)
	v_mfma_f32_32x32x16_bf16 v[50:65], v[22:25], v[72:75], v[50:65]
	s_waitcnt vmcnt(1) lgkmcnt(0)
	v_mfma_f32_32x32x16_bf16 v[50:65], v[18:21], v[76:79], v[50:65]
	ds_read_b128 v[18:21], v26 offset:96
	s_waitcnt vmcnt(0) lgkmcnt(0)
	v_mfma_f32_32x32x16_bf16 v[50:65], v[18:21], v[80:83], v[50:65]
	v_add_u32_e32 v18, s23, v99
	v_mad_u64_u32 v[92:93], s[24:25], v18, s3, v[84:85]
	v_mov_b64_e32 v[32:33], v[16:17]
	v_mov_b32_e32 v93, 0
	s_mov_b32 s23, 0
	s_mov_b32 s24, 0
	s_nop 5
	v_mov_b64_e32 v[30:31], v[14:15]
	v_mov_b64_e32 v[28:29], v[12:13]
	v_mov_b64_e32 v[26:27], v[10:11]
	v_mov_b64_e32 v[24:25], v[8:9]
	v_mov_b64_e32 v[22:23], v[6:7]
	v_mov_b64_e32 v[20:21], v[4:5]
	v_mov_b64_e32 v[18:19], v[2:3]

; __device__ __forceinline__ void attn_unit(LAS unsigned char* lds, const bf16* PROJ, bf16* DA, const float* sinkl, int unit, int tid, int wid, int lane) {
;     ...
;             const float kmin = fmaxf(fb - 128.0f, (float)(-sb0)), kmax = fminf(fb + 128.0f, (float)(SEQ - 1 - sb0));
;             const float kmid = 0.5f * (kmin + kmax), khw = 0.5f * (kmax - kmin);
;             float mx = NEG;
; #pragma unroll
;             for (int r = 0; r < 16; ++r) { const float kr = (float)((r & 3) + 8 * (r >> 2)); p[r] = p[r] - slope2 * fabsf(fb - kr); }
;             if ((i == 0) || (i == 8) || edge_n) {
; #pragma unroll
;                 for (int r = 0; r < 16; ++r) { const float kr = (float)((r & 3) + 8 * (r >> 2)); p[r] = (fabsf(kr - kmid) <= khw) ? p[r] : NEG; }
;             }
; #pragma unroll
;             for (int r = 0; r < 16; ++r) mx = fmaxf(mx, p[r]);
;             { const auto rr = __builtin_amdgcn_permlane32_swap(__float_as_uint(mx), __float_as_uint(mx), false, false); mx = fmaxf(__uint_as_float(rr[0]), __uint_as_float(rr[1])); }
;             if (__any(mx > mrun + 8.0f)) {
;                 const float mnew = fmaxf(mrun, mx), alpha = __builtin_amdgcn_exp2f(mrun - mnew);
;                 mrun = mnew; l *= alpha;
; #pragma unroll
;                 for (int r = 0; r < 16; ++r) { o0[r] *= alpha; o1[r] *= alpha; }
;             }
;             float ps = 0.f;
; #pragma unroll
;             for (int r = 0; r < 16; ++r) { p[r] = __builtin_amdgcn_exp2f(p[r] - mrun); ps += p[r]; }
.Lalibi_mixed:
	v_fma_f32 v50, -v162, |v104|, v50
	v_subrev_f32_e32 v164, 0x3f800000, v104
	v_fma_f32 v51, -v163, |v164|, v51
	v_subrev_f32_e32 v165, 0x40000000, v104
	v_fma_f32 v52, -v162, |v165|, v52
	v_subrev_f32_e32 v164, 0x40400000, v104
	v_fma_f32 v53, -v163, |v164|, v53
	v_subrev_f32_e32 v165, 0x41000000, v104
	v_fma_f32 v54, -v162, |v165|, v54
	v_subrev_f32_e32 v164, 0x41100000, v104
	v_fma_f32 v55, -v163, |v164|, v55
	v_subrev_f32_e32 v165, 0x41200000, v104
	v_fma_f32 v56, -v162, |v165|, v56
	v_subrev_f32_e32 v164, 0x41300000, v104
	v_fma_f32 v57, -v163, |v164|, v57
	v_subrev_f32_e32 v165, 0x41800000, v104
	v_fma_f32 v58, -v162, |v165|, v58
	v_subrev_f32_e32 v164, 0x41880000, v104
	v_fma_f32 v59, -v163, |v164|, v59
	v_subrev_f32_e32 v165, 0x41900000, v104
	v_fma_f32 v60, -v162, |v165|, v60
	v_subrev_f32_e32 v164, 0x41980000, v104
	v_fma_f32 v61, -v163, |v164|, v61
	v_subrev_f32_e32 v165, 0x41c00000, v104
	v_fma_f32 v62, -v162, |v165|, v62
	v_subrev_f32_e32 v164, 0x41c80000, v104
	v_fma_f32 v63, -v163, |v164|, v63
	v_subrev_f32_e32 v165, 0x41d00000, v104
	v_fma_f32 v64, -v162, |v165|, v64
	v_subrev_f32_e32 v164, 0x41d80000, v104
	v_fma_f32 v65, -v163, |v164|, v65
	v_mov_b32_e32 v146, 0
.Lalibi_done:
	s_cmp_eq_u32 s78, 0
	s_cbranch_scc1 .Ledge_lo
	s_cmp_eq_u32 s78, 31
	s_cbranch_scc1 .Ledge_hi
.LBB0_387:
	v_max3_f32 v104, v50, s22, v51
	v_max3_f32 v104, v104, v52, v53
	v_max3_f32 v104, v104, v54, v55
	v_max3_f32 v104, v104, v56, v57
	v_max3_f32 v104, v104, v58, v59
	v_max3_f32 v104, v104, v60, v61
	v_max3_f32 v104, v104, v62, v63
	v_max3_f32 v104, v104, v64, v65
	v_mov_b32_e32 v105, v104
	s_nop 1
	v_permlane32_swap_b32_e32 v104, v105
	v_max_f32_e32 v105, v105, v105
	v_max_f32_e32 v104, v104, v104
	v_max_f32_e32 v104, v104, v105
	v_sub_f32_e32 v104, v104, v146
	v_add_f32_e32 v105, 0x41000000, v103
	v_cmp_gt_f32_e32 vcc, v104, v105
	s_cbranch_vccz .LBB0_389
	v_max_f32_e32 v104, v104, v104
	v_max_f32_e32 v105, v103, v103
	v_max_f32_e32 v105, v105, v104
	v_sub_f32_e32 v103, v103, v105
	v_exp_f32_e32 v104, v103
	v_mov_b32_e32 v103, v105
	v_pk_mul_f32 v[32:33], v[32:33], v[104:105] op_sel_hi:[1,0]
	v_pk_mul_f32 v[30:31], v[30:31], v[104:105] op_sel_hi:[1,0]
	v_pk_mul_f32 v[28:29], v[28:29], v[104:105] op_sel_hi:[1,0]
	v_pk_mul_f32 v[26:27], v[26:27], v[104:105] op_sel_hi:[1,0]
	v_pk_mul_f32 v[24:25], v[24:25], v[104:105] op_sel_hi:[1,0]
	v_pk_mul_f32 v[22:23], v[22:23], v[104:105] op_sel_hi:[1,0]
	v_pk_mul_f32 v[20:21], v[20:21], v[104:105] op_sel_hi:[1,0]
	v_pk_mul_f32 v[18:19], v[18:19], v[104:105] op_sel_hi:[1,0]
	v_pk_mul_f32 v[16:17], v[16:17], v[104:105] op_sel_hi:[1,0]
	v_pk_mul_f32 v[14:15], v[14:15], v[104:105] op_sel_hi:[1,0]
	v_pk_mul_f32 v[12:13], v[12:13], v[104:105] op_sel_hi:[1,0]
	v_pk_mul_f32 v[10:11], v[10:11], v[104:105] op_sel_hi:[1,0]
	v_pk_mul_f32 v[8:9], v[8:9], v[104:105] op_sel_hi:[1,0]
	v_pk_mul_f32 v[6:7], v[6:7], v[104:105] op_sel_hi:[1,0]
	v_pk_mul_f32 v[4:5], v[4:5], v[104:105] op_sel_hi:[1,0]
	v_pk_mul_f32 v[2:3], v[2:3], v[104:105] op_sel_hi:[1,0]
	v_mul_f32_e32 v93, v93, v104

; #define ATT_QK(dst, cblk) do { _Pragma("unroll") for (int r = 0; r < 16; ++r) dst[r] = 0.f; \
;             _Pragma("unroll") for (int ks = 0; ks < 4; ++ks) { const bf16x8 kf = *(const LAS bf16x8*)(Ks + ((cblk) + r32) * KS_PITCH + ks * 16 + hi * 8); \
;                 dst = __builtin_amdgcn_mfma_f32_32x32x16_bf16(kf, qf[ks], dst, 0, 0, 0); } } while (0)
; __device__ __forceinline__ void attn_unit(LAS unsigned char* lds, const bf16* PROJ, bf16* DA, const float* sinkl, int unit, int tid, int wid, int lane) {
;     ...
;         for (int i = 0; i < 9; ++i) {
;             const int c0 = a0 + 32 * i;
;             f32x16 p = pn;
;             if (i < 8) ATT_QK(pn, c0 + 32);
;             const float fb = fb0 - (float)(32 * i);
.Lblk_tail:
	s_cmpk_eq_i32 s23, 0xfee0
	v_add_u32_e32 v92, 0x1200, v92
	s_cbranch_scc1 .LBB0_379
	s_cmp_gt_i32 s23, 0xffffff80
	s_cbranch_scc1 .Lqa_pos
	s_cmp_eq_u32 s23, 0xffffff80
	s_cbranch_scc1 .Lqa_zero
	s_cmp_eq_u32 s23, 0xffffff00
	s_cbranch_scc1 .Lqa_c8
	v_mfma_f32_32x32x16_bf16 v[50:65], v[174:177], v[68:71], v[220:235]
	s_branch .Lqa_done
.Lqa_c8:
	v_mfma_f32_32x32x16_bf16 v[50:65], v[174:177], v[68:71], v[106:121]
	s_branch .Lqa_done

; #define ATT_QK(dst, cblk) do { _Pragma("unroll") for (int r = 0; r < 16; ++r) dst[r] = 0.f; \
;             _Pragma("unroll") for (int ks = 0; ks < 4; ++ks) { const bf16x8 kf = *(const LAS bf16x8*)(Ks + ((cblk) + r32) * KS_PITCH + ks * 16 + hi * 8); \
;                 dst = __builtin_amdgcn_mfma_f32_32x32x16_bf16(kf, qf[ks], dst, 0, 0, 0); } } while (0)
; __device__ __forceinline__ void attn_unit(LAS unsigned char* lds, const bf16* PROJ, bf16* DA, const float* sinkl, int unit, int tid, int wid, int lane) {
;     ...
;             if (i < 8) ATT_QK(pn, c0 + 32);
;             const float fb = fb0 - (float)(32 * i);
;             const int sb0 = s0 + c0 + 4 * hi;
;             const float kmin = fmaxf(fb - 128.0f, (float)(-sb0)), kmax = fminf(fb + 128.0f, (float)(SEQ - 1 - sb0));
;             const float kmid = 0.5f * (kmin + kmax), khw = 0.5f * (kmax - kmin);
;             float mx = NEG;
; #pragma unroll
;             for (int r = 0; r < 16; ++r) { const float kr = (float)((r & 3) + 8 * (r >> 2)); p[r] = p[r] - slope2 * fabsf(fb - kr); }
;             if ((i == 0) || (i == 8) || edge_n) {
.Lqa_done:
	v_mfma_f32_32x32x16_bf16 v[50:65], v[178:181], v[72:75], v[50:65]
	v_mfma_f32_32x32x16_bf16 v[50:65], v[182:185], v[76:79], v[50:65]
	v_mfma_f32_32x32x16_bf16 v[50:65], v[186:189], v[80:83], v[50:65]
	s_nop 5
	s_branch .LBB0_381
.Ledge_lo:
	s_sub_i32 s88, s89, s23
	s_cmp_le_i32 s88, 0x60
	s_cbranch_scc1 .Lblk_skip
	s_branch .Ledge_valid

; __device__ __forceinline__ void attn_unit(LAS unsigned char* lds, const bf16* PROJ, bf16* DA, const float* sinkl, int unit, int tid, int wid, int lane) {
;     ...
;             if ((i == 0) || (i == 8) || edge_n) {
; #pragma unroll
;                 for (int r = 0; r < 16; ++r) { const float kr = (float)((r & 3) + 8 * (r >> 2)); p[r] = (fabsf(kr - kmid) <= khw) ? p[r] : NEG; }
;             }
; #pragma unroll
;             for (int r = 0; r < 16; ++r) mx = fmaxf(mx, p[r]);
.Ledge_valid:
	s_branch .LBB0_387
